# removed duplicate grid barrier between mixer and out-projection and the final barrier after the last layer
# speedup vs baseline: 1.0156x; 1.0156x over previous
.LBB0_1126:
.LBB0_1184:
	s_mov_b64 s[4:5], s[0:1]
	s_load_dword s4, s[4:5], 0x68
	s_waitcnt lgkmcnt(0)
	s_cmp_eq_u32 s4, 0
	s_cbranch_scc1 .LBB0_1242
	s_mov_b64 s[4:5], s[0:1]
	s_load_dword s5, s[4:5], 0x60
	s_add_i32 s4, s47, 3
	s_waitcnt lgkmcnt(0)
	s_cmp_gt_i32 s5, s4
	s_cbranch_scc1 .LBB0_1242
	s_mov_b64 s[6:7], s[0:1]
	s_load_dword s5, s[6:7], 0x64
	s_waitcnt lgkmcnt(0)
	s_cmp_ge_i32 s4, s5
	s_cbranch_scc1 .LBB0_1242
	s_mov_b64 s[4:5], s[0:1]
	s_load_dword s5, s[4:5], 0x60
	s_add_i32 s4, s47, 4
	s_waitcnt lgkmcnt(0)
	s_cmp_gt_i32 s5, s4
	s_cbranch_scc1 .LBB0_1242
	s_mov_b64 s[6:7], s[0:1]
	s_load_dword s5, s[6:7], 0x64
	s_waitcnt lgkmcnt(0)
	s_cmp_ge_i32 s4, s5
	s_cbranch_scc1 .LBB0_1242
	s_mov_b64 s[6:7], s[0:1]
	s_waitcnt vmcnt(0)
	s_waitcnt vmcnt(0)
	s_barrier
	s_and_saveexec_b64 s[4:5], s[10:11]
	s_cbranch_execz .LBB0_1241
	v_readlane_b32 s9, v254, 46
	s_load_dwordx2 s[6:7], s[6:7], 0x58
	s_getreg_b32 s8, hwreg(HW_REG_XCC_ID, 0, 4)
	v_mov_b32_e32 v0, s9
	s_waitcnt vmcnt(0) expcnt(0) lgkmcnt(0)
	ds_read_b32 v2, v0
	v_readlane_b32 s9, v254, 47
	s_and_b32 s26, s8, 15
	s_waitcnt lgkmcnt(0)
	v_cmp_ne_u32_e32 vcc, 0, v2
	v_mov_b32_e32 v0, s9
	ds_read_b32 v0, v0
	s_cbranch_vccnz .LBB0_1205
	s_load_dwordx2 s[14:15], s[52:53], 0x0
	s_load_dword s13, s[52:53], 0x8
	s_add_u32 s8, s6, 0x1b1c1200
	s_addc_u32 s9, s7, 0
	s_add_u32 s12, s6, 0x1b1c1400
	s_waitcnt lgkmcnt(0)
	s_mul_i32 s94, s15, s14
	s_mul_i32 s94, s94, s13
	s_addc_u32 s13, s7, 0
	s_add_u32 s14, s6, 0x1b1c1500
	s_addc_u32 s15, s7, 0
	s_add_u32 s50, s6, 0x1b1c1600
	s_addc_u32 s51, s7, 0
	s_add_u32 s22, s6, 0x1b1c1700
	s_addc_u32 s23, s7, 0
	s_add_u32 s56, s6, 0x1b1c1800
	s_addc_u32 s57, s7, 0
	s_add_u32 s76, s6, 0x1b1c1900
	s_addc_u32 s77, s7, 0
	s_add_u32 s80, s6, 0x1b1c1a00
	s_addc_u32 s81, s7, 0
	s_add_u32 s82, s6, 0x1b1c1b00
	s_addc_u32 s83, s7, 0
	s_add_u32 s84, s6, 0x1b1c1c00
	s_addc_u32 s85, s7, 0
	s_mov_b32 s46, s86
	s_add_u32 s86, s6, 0x1b1c1d00
	s_addc_u32 s87, s7, 0
	s_add_u32 s88, s6, 0x1b1c1e00
	s_addc_u32 s89, s7, 0
	s_add_u32 s90, s6, 0x1b1c1f00
	s_addc_u32 s91, s7, 0
	s_add_u32 s38, s6, 0x1b1c2000
	s_addc_u32 s39, s7, 0
	s_add_u32 s40, s6, 0x1b1c2100
	s_addc_u32 s41, s7, 0
	s_add_u32 s44, s6, 0x1b1c2200
	s_addc_u32 s45, s7, 0
	s_add_u32 s42, s6, 0x1b1c2300
	s_addc_u32 s43, s7, 0
	s_mov_b32 s95, 1
	s_branch .LBB0_1193

.LBB0_1335:
	s_cmp_eq_u32 s86, 3
	s_cbranch_scc1 .LBB0_330
	s_mov_b64 s[4:5], s[0:1]
	s_load_dword s4, s[4:5], 0x68
	s_waitcnt lgkmcnt(0)
	s_cmp_eq_u32 s4, 0
	s_cbranch_scc1 .LBB0_330
	s_mov_b64 s[4:5], s[0:1]
	s_load_dword s4, s[4:5], 0x60
	s_waitcnt lgkmcnt(0)
	s_cmp_gt_i32 s4, s42
	s_cbranch_scc1 .LBB0_330
	s_mov_b64 s[4:5], s[0:1]
	s_load_dword s4, s[4:5], 0x64
	s_waitcnt lgkmcnt(0)
	s_cmp_ge_i32 s42, s4
	s_cbranch_scc1 .LBB0_330
	s_mov_b64 s[4:5], s[0:1]
	s_load_dword s5, s[4:5], 0x60
	s_add_i32 s4, s47, 5
	s_waitcnt lgkmcnt(0)
	s_cmp_gt_i32 s5, s4
	s_cbranch_scc1 .LBB0_330
	s_mov_b64 s[6:7], s[0:1]
	s_load_dword s5, s[6:7], 0x64
	s_waitcnt lgkmcnt(0)
	s_cmp_ge_i32 s4, s5
	s_cbranch_scc1 .LBB0_330
	s_mov_b64 s[6:7], s[0:1]
	s_waitcnt vmcnt(0)
	s_waitcnt vmcnt(0)
	s_barrier
	s_and_saveexec_b64 s[4:5], s[10:11]
	s_cbranch_execz .LBB0_329
	v_readlane_b32 s9, v254, 46
	s_load_dwordx2 s[6:7], s[6:7], 0x58
	s_getreg_b32 s8, hwreg(HW_REG_XCC_ID, 0, 4)
	v_mov_b32_e32 v0, s9
	s_waitcnt vmcnt(0) expcnt(0) lgkmcnt(0)
	ds_read_b32 v2, v0
	v_readlane_b32 s9, v254, 47
	s_and_b32 s26, s8, 15
	s_waitcnt lgkmcnt(0)
	v_cmp_ne_u32_e32 vcc, 0, v2
	v_mov_b32_e32 v0, s9
	ds_read_b32 v0, v0
	s_cbranch_vccnz .LBB0_1356
	s_load_dwordx2 s[14:15], s[52:53], 0x0
	s_load_dword s13, s[52:53], 0x8
	s_add_u32 s8, s6, 0x1b1c1200
	s_addc_u32 s9, s7, 0
	s_add_u32 s12, s6, 0x1b1c1400
	s_waitcnt lgkmcnt(0)
	s_mul_i32 s94, s15, s14
	s_mul_i32 s94, s94, s13
	s_addc_u32 s13, s7, 0
	s_add_u32 s14, s6, 0x1b1c1500
	s_addc_u32 s15, s7, 0
	s_add_u32 s50, s6, 0x1b1c1600
	s_addc_u32 s51, s7, 0
	s_add_u32 s22, s6, 0x1b1c1700
	s_addc_u32 s23, s7, 0
	s_add_u32 s56, s6, 0x1b1c1800
	s_addc_u32 s57, s7, 0
	s_add_u32 s76, s6, 0x1b1c1900
	s_addc_u32 s77, s7, 0
	s_add_u32 s80, s6, 0x1b1c1a00
	s_addc_u32 s81, s7, 0
	s_add_u32 s82, s6, 0x1b1c1b00
	s_addc_u32 s83, s7, 0
	s_add_u32 s84, s6, 0x1b1c1c00
	s_addc_u32 s85, s7, 0
	s_mov_b32 s46, s86
	s_add_u32 s86, s6, 0x1b1c1d00
	s_addc_u32 s87, s7, 0
	s_add_u32 s88, s6, 0x1b1c1e00
	s_addc_u32 s89, s7, 0
	s_add_u32 s90, s6, 0x1b1c1f00
	s_addc_u32 s91, s7, 0
	s_add_u32 s38, s6, 0x1b1c2000
	s_addc_u32 s39, s7, 0
	s_add_u32 s40, s6, 0x1b1c2100
	s_addc_u32 s41, s7, 0
	s_add_u32 s44, s6, 0x1b1c2200
	s_addc_u32 s45, s7, 0
	s_add_u32 s42, s6, 0x1b1c2300
	s_addc_u32 s43, s7, 0
	s_mov_b32 s95, 1
	s_branch .LBB0_1344
